# flattened grid barrier with the post-invalidate vmcnt(0) wait restored before the block barrier (memory-model-complete acquire)
# speedup vs baseline: 1.0014x; 1.0014x over previous
; DEV unsigned xb_ld(unsigned* p) { return __hip_atomic_load(p, __ATOMIC_RELAXED, __HIP_MEMORY_SCOPE_AGENT); }
; #define XB_SPIN(cond, bar) do { unsigned _sp = 0; while (cond) { __builtin_amdgcn_s_sleep(1); \
;     if ((++_sp & 255u) == 0u) { if (xb_ld(&(bar)[XB_TMO])) break; if (_sp > XB_SPIN_CAP) { atomicAdd(&(bar)[XB_TMO], 1u); break; } } } } while (0)
; DEV void xcd_barrier(const XcdBarrier& b) {
;     ...
;     } else {
;       XB_SPIN(xb_ld(&bar[XB_XGEN(b.x)]) == gen, bar);
;       __builtin_amdgcn_fence(__ATOMIC_ACQUIRE, "agent");
;       asm volatile("s_waitcnt vmcnt(0)" ::: "memory");
;     }
;   }
;   __syncthreads();
Lxb1_done:
	buffer_inv sc1
	s_waitcnt vmcnt(0)

; DEV unsigned xb_ld(unsigned* p) { return __hip_atomic_load(p, __ATOMIC_RELAXED, __HIP_MEMORY_SCOPE_AGENT); }
; #define XB_SPIN(cond, bar) do { unsigned _sp = 0; while (cond) { __builtin_amdgcn_s_sleep(1); \
;     if ((++_sp & 255u) == 0u) { if (xb_ld(&(bar)[XB_TMO])) break; if (_sp > XB_SPIN_CAP) { atomicAdd(&(bar)[XB_TMO], 1u); break; } } } } while (0)
; DEV void xcd_barrier(const XcdBarrier& b) {
;     ...
;     } else {
;       XB_SPIN(xb_ld(&bar[XB_XGEN(b.x)]) == gen, bar);
;       __builtin_amdgcn_fence(__ATOMIC_ACQUIRE, "agent");
;       asm volatile("s_waitcnt vmcnt(0)" ::: "memory");
;     }
;   }
;   __syncthreads();
Lxb2_done:
	buffer_inv sc1
	s_waitcnt vmcnt(0)
	s_branch .LBB0_325

; DEV unsigned xb_ld(unsigned* p) { return __hip_atomic_load(p, __ATOMIC_RELAXED, __HIP_MEMORY_SCOPE_AGENT); }
; #define XB_SPIN(cond, bar) do { unsigned _sp = 0; while (cond) { __builtin_amdgcn_s_sleep(1); \
;     if ((++_sp & 255u) == 0u) { if (xb_ld(&(bar)[XB_TMO])) break; if (_sp > XB_SPIN_CAP) { atomicAdd(&(bar)[XB_TMO], 1u); break; } } } } while (0)
; DEV void xcd_barrier(const XcdBarrier& b) {
;     ...
;     } else {
;       XB_SPIN(xb_ld(&bar[XB_XGEN(b.x)]) == gen, bar);
;       __builtin_amdgcn_fence(__ATOMIC_ACQUIRE, "agent");
;       asm volatile("s_waitcnt vmcnt(0)" ::: "memory");
;     }
;   }
;   __syncthreads();
Lxb3_done:
	buffer_inv sc1
	s_waitcnt vmcnt(0)

; DEV unsigned xb_ld(unsigned* p) { return __hip_atomic_load(p, __ATOMIC_RELAXED, __HIP_MEMORY_SCOPE_AGENT); }
; #define XB_SPIN(cond, bar) do { unsigned _sp = 0; while (cond) { __builtin_amdgcn_s_sleep(1); \
;     if ((++_sp & 255u) == 0u) { if (xb_ld(&(bar)[XB_TMO])) break; if (_sp > XB_SPIN_CAP) { atomicAdd(&(bar)[XB_TMO], 1u); break; } } } } while (0)
; DEV void xcd_barrier(const XcdBarrier& b) {
;     ...
;     } else {
;       XB_SPIN(xb_ld(&bar[XB_XGEN(b.x)]) == gen, bar);
;       __builtin_amdgcn_fence(__ATOMIC_ACQUIRE, "agent");
;       asm volatile("s_waitcnt vmcnt(0)" ::: "memory");
;     }
;   }
;   __syncthreads();
Lxb4_done:
	buffer_inv sc1
	s_waitcnt vmcnt(0)

; DEV unsigned xb_ld(unsigned* p) { return __hip_atomic_load(p, __ATOMIC_RELAXED, __HIP_MEMORY_SCOPE_AGENT); }
; #define XB_SPIN(cond, bar) do { unsigned _sp = 0; while (cond) { __builtin_amdgcn_s_sleep(1); \
;     if ((++_sp & 255u) == 0u) { if (xb_ld(&(bar)[XB_TMO])) break; if (_sp > XB_SPIN_CAP) { atomicAdd(&(bar)[XB_TMO], 1u); break; } } } } while (0)
; DEV void xcd_barrier(const XcdBarrier& b) {
;     ...
;     } else {
;       XB_SPIN(xb_ld(&bar[XB_XGEN(b.x)]) == gen, bar);
;       __builtin_amdgcn_fence(__ATOMIC_ACQUIRE, "agent");
;       asm volatile("s_waitcnt vmcnt(0)" ::: "memory");
;     }
;   }
;   __syncthreads();
Lxb5_done:
	buffer_inv sc1
	s_waitcnt vmcnt(0)

; DEV unsigned xb_ld(unsigned* p) { return __hip_atomic_load(p, __ATOMIC_RELAXED, __HIP_MEMORY_SCOPE_AGENT); }
; #define XB_SPIN(cond, bar) do { unsigned _sp = 0; while (cond) { __builtin_amdgcn_s_sleep(1); \
;     if ((++_sp & 255u) == 0u) { if (xb_ld(&(bar)[XB_TMO])) break; if (_sp > XB_SPIN_CAP) { atomicAdd(&(bar)[XB_TMO], 1u); break; } } } } while (0)
; DEV void xcd_barrier(const XcdBarrier& b) {
;     ...
;     } else {
;       XB_SPIN(xb_ld(&bar[XB_XGEN(b.x)]) == gen, bar);
;       __builtin_amdgcn_fence(__ATOMIC_ACQUIRE, "agent");
;       asm volatile("s_waitcnt vmcnt(0)" ::: "memory");
;     }
;   }
;   __syncthreads();
Lxb6_done:
	buffer_inv sc1
	s_waitcnt vmcnt(0)

; DEV unsigned xb_ld(unsigned* p) { return __hip_atomic_load(p, __ATOMIC_RELAXED, __HIP_MEMORY_SCOPE_AGENT); }
; #define XB_SPIN(cond, bar) do { unsigned _sp = 0; while (cond) { __builtin_amdgcn_s_sleep(1); \
;     if ((++_sp & 255u) == 0u) { if (xb_ld(&(bar)[XB_TMO])) break; if (_sp > XB_SPIN_CAP) { atomicAdd(&(bar)[XB_TMO], 1u); break; } } } } while (0)
; DEV void xcd_barrier(const XcdBarrier& b) {
;     ...
;     } else {
;       XB_SPIN(xb_ld(&bar[XB_XGEN(b.x)]) == gen, bar);
;       __builtin_amdgcn_fence(__ATOMIC_ACQUIRE, "agent");
;       asm volatile("s_waitcnt vmcnt(0)" ::: "memory");
;     }
;   }
;   __syncthreads();
Lxb7_done:
	buffer_inv sc1
	s_waitcnt vmcnt(0)

; DEV unsigned xb_ld(unsigned* p) { return __hip_atomic_load(p, __ATOMIC_RELAXED, __HIP_MEMORY_SCOPE_AGENT); }
; #define XB_SPIN(cond, bar) do { unsigned _sp = 0; while (cond) { __builtin_amdgcn_s_sleep(1); \
;     if ((++_sp & 255u) == 0u) { if (xb_ld(&(bar)[XB_TMO])) break; if (_sp > XB_SPIN_CAP) { atomicAdd(&(bar)[XB_TMO], 1u); break; } } } } while (0)
; DEV void xcd_barrier(const XcdBarrier& b) {
;     ...
;     } else {
;       XB_SPIN(xb_ld(&bar[XB_XGEN(b.x)]) == gen, bar);
;       __builtin_amdgcn_fence(__ATOMIC_ACQUIRE, "agent");
;       asm volatile("s_waitcnt vmcnt(0)" ::: "memory");
;     }
;   }
;   __syncthreads();
Lxb8_done:
	buffer_inv sc1
	s_waitcnt vmcnt(0)
